# sample attention compressed branch: later K-row / V^T load batches requested together with the first (spare registers, copied in at use) instead of 6 serialized load+vmcnt(0) steps
# speedup vs baseline: 1.0042x; 1.0008x over previous
; __device__ __forceinline__ void nsa_sample_unit(Frame& F, int l, int unit, int part_id) {
;     ...
;         const int n = tid & 255, gp = tid >> 8;
;         const bf16_t* kr = (const bf16_t*)(F.ws + WS_KCS) + ((size_t)(b * 4 + kvh) * 256 + n) * 64;
;         float d0 = 0.f, d1 = 0.f;
; #pragma unroll
;         for (int j = 0; j < 8; ++j) { const u32x4 x = *(const u32x4*)(kr + 8 * j); float kf[8]; unpack8(x, kf);
; #pragma unroll
;             for (int e = 0; e < 8; ++e) { d0 += kf[e] * qv[(2 * gp) * 64 + 8 * j + e]; d1 += kf[e] * qv[(2 * gp + 1) * 64 + 8 * j + e]; } }
;         sc[(2 * gp) * 1040 + n] = d0 * 0.125f; sc[(2 * gp + 1) * 1040 + n] = d1 * 0.125f;
.LBB0_992:
	s_and_b64 vcc, exec, s[22:23]
	s_cbranch_vccz .LBB0_879
	s_or_b32 s4, s16, s8
	s_lshl_b32 s4, s4, 15
	v_lshl_add_u64 v[14:15], v[106:107], 0, s[4:5]
	global_load_dwordx4 v[2:5], v[14:15], off offset:48
	global_load_dwordx4 v[6:9], v[14:15], off offset:32
	global_load_dwordx4 v[10:13], v[14:15], off offset:16
	global_load_dwordx4 v[16:19], v[14:15], off
	global_load_dwordx4 v[60:63], v[14:15], off offset:112
	global_load_dwordx4 v[64:67], v[14:15], off offset:96
	global_load_dwordx4 v[68:71], v[14:15], off offset:80
	global_load_dwordx4 v[72:75], v[14:15], off offset:64
	ds_read_b128 v[20:23], v136
	ds_read_b128 v[24:27], v136 offset:16
	ds_read_b128 v[28:31], v136 offset:32
	ds_read_b128 v[32:35], v136 offset:48
	ds_read_b128 v[36:39], v136 offset:256
	s_mov_b64 s[22:23], 0
	s_waitcnt vmcnt(4)
	v_lshlrev_b32_e32 v40, 16, v16
	v_and_b32_e32 v16, 0xffff0000, v16
	v_lshlrev_b32_e32 v42, 16, v18
	v_and_b32_e32 v43, 0xffff0000, v18
	s_waitcnt lgkmcnt(4)
	v_fma_f32 v18, v20, v40, 0
	v_lshlrev_b32_e32 v41, 16, v17
	v_fmac_f32_e32 v18, v21, v16
	v_and_b32_e32 v17, 0xffff0000, v17
	v_fmac_f32_e32 v18, v22, v41
	v_fmac_f32_e32 v18, v23, v17
	ds_read_b128 v[20:23], v136 offset:272
	v_lshlrev_b32_e32 v44, 16, v19
	v_and_b32_e32 v45, 0xffff0000, v19
	s_waitcnt lgkmcnt(1)
	v_fma_f32 v19, v36, v40, 0
	v_fmac_f32_e32 v19, v37, v16
	v_fmac_f32_e32 v19, v38, v41
	v_fmac_f32_e32 v19, v39, v17
	s_waitcnt lgkmcnt(0)
	v_fmac_f32_e32 v19, v20, v42
	v_fmac_f32_e32 v19, v21, v43
	v_fmac_f32_e32 v18, v24, v42
	v_fmac_f32_e32 v19, v22, v44
	v_fmac_f32_e32 v18, v25, v43
	v_fmac_f32_e32 v19, v23, v45
	v_lshlrev_b32_e32 v16, 16, v10
	v_and_b32_e32 v17, 0xffff0000, v10
	v_lshlrev_b32_e32 v20, 16, v11
	v_and_b32_e32 v21, 0xffff0000, v11
	v_lshlrev_b32_e32 v22, 16, v12
	v_and_b32_e32 v23, 0xffff0000, v12
	v_lshlrev_b32_e32 v24, 16, v13
	v_and_b32_e32 v25, 0xffff0000, v13
	ds_read_b128 v[10:13], v136 offset:288
	v_fmac_f32_e32 v18, v26, v44
	v_fmac_f32_e32 v18, v27, v45
	v_fmac_f32_e32 v18, v28, v16
	v_fmac_f32_e32 v18, v29, v17
	s_waitcnt lgkmcnt(0)
	v_fmac_f32_e32 v19, v10, v16
	v_fmac_f32_e32 v19, v11, v17
	v_fmac_f32_e32 v19, v12, v20
	v_fmac_f32_e32 v19, v13, v21
	ds_read_b128 v[10:13], v136 offset:304
	v_fmac_f32_e32 v18, v30, v20
	v_fmac_f32_e32 v18, v31, v21
	v_fmac_f32_e32 v18, v32, v22
	v_fmac_f32_e32 v18, v33, v23
	s_waitcnt lgkmcnt(0)
	v_fmac_f32_e32 v19, v10, v22
	v_fmac_f32_e32 v19, v11, v23
	v_fmac_f32_e32 v18, v34, v24
	v_fmac_f32_e32 v19, v12, v24
	v_fmac_f32_e32 v18, v35, v25
	v_fmac_f32_e32 v19, v13, v25
	v_lshlrev_b32_e32 v16, 16, v6
	v_and_b32_e32 v17, 0xffff0000, v6
	v_lshlrev_b32_e32 v20, 16, v7
	v_and_b32_e32 v21, 0xffff0000, v7
	v_lshlrev_b32_e32 v22, 16, v8
	v_and_b32_e32 v23, 0xffff0000, v8
	v_lshlrev_b32_e32 v24, 16, v9
	v_and_b32_e32 v25, 0xffff0000, v9
	ds_read_b128 v[6:9], v136 offset:64
	ds_read_b128 v[10:13], v136 offset:320
	s_waitcnt lgkmcnt(1)
	v_fmac_f32_e32 v18, v6, v16
	s_waitcnt lgkmcnt(0)
	v_fmac_f32_e32 v19, v10, v16
	v_fmac_f32_e32 v19, v11, v17
	v_fmac_f32_e32 v19, v12, v20
	v_fmac_f32_e32 v19, v13, v21
	ds_read_b128 v[10:13], v136 offset:336
	v_fmac_f32_e32 v18, v7, v17
	v_fmac_f32_e32 v18, v8, v20
	v_fmac_f32_e32 v18, v9, v21
	ds_read_b128 v[6:9], v136 offset:80
	s_waitcnt lgkmcnt(1)
	v_fmac_f32_e32 v19, v10, v22
	v_fmac_f32_e32 v19, v11, v23
	v_fmac_f32_e32 v19, v12, v24
	v_fmac_f32_e32 v19, v13, v25
	v_lshlrev_b32_e32 v10, 16, v2
	v_and_b32_e32 v11, 0xffff0000, v2
	v_lshlrev_b32_e32 v12, 16, v3
	v_and_b32_e32 v13, 0xffff0000, v3
	v_lshlrev_b32_e32 v16, 16, v4
	v_and_b32_e32 v17, 0xffff0000, v4
	v_lshlrev_b32_e32 v20, 16, v5
	v_and_b32_e32 v21, 0xffff0000, v5
	ds_read_b128 v[2:5], v136 offset:96
	s_waitcnt lgkmcnt(1)
	v_fmac_f32_e32 v18, v6, v22
	v_fmac_f32_e32 v18, v7, v23
	v_fmac_f32_e32 v18, v8, v24
	v_fmac_f32_e32 v18, v9, v25
	ds_read_b128 v[6:9], v136 offset:352
	s_waitcnt lgkmcnt(1)
	v_fmac_f32_e32 v18, v2, v10
	v_fmac_f32_e32 v18, v3, v11
	v_fmac_f32_e32 v18, v4, v12
	v_fmac_f32_e32 v18, v5, v13
	ds_read_b128 v[2:5], v136 offset:112
	s_waitcnt lgkmcnt(1)
	v_fmac_f32_e32 v19, v6, v10
	v_fmac_f32_e32 v19, v7, v11
	v_fmac_f32_e32 v19, v8, v12
	v_fmac_f32_e32 v19, v9, v13
	ds_read_b128 v[6:9], v136 offset:368
	s_waitcnt lgkmcnt(1)
	v_fmac_f32_e32 v18, v2, v16
	v_fmac_f32_e32 v18, v3, v17
	v_fmac_f32_e32 v18, v4, v20
	v_fmac_f32_e32 v18, v5, v21
	s_waitcnt lgkmcnt(0)
	v_fmac_f32_e32 v19, v6, v16
	v_fmac_f32_e32 v19, v7, v17
	v_fmac_f32_e32 v19, v8, v20
	v_fmac_f32_e32 v19, v9, v21
	s_waitcnt vmcnt(0)
; __device__ __forceinline__ void nsa_sample_unit(Frame& F, int l, int unit, int part_id) {
;     ...
;         for (int j = 0; j < 8; ++j) { const u32x4 x = *(const u32x4*)(kr + 8 * j); float kf[8]; unpack8(x, kf);
; #pragma unroll
;             for (int e = 0; e < 8; ++e) { d0 += kf[e] * qv[(2 * gp) * 64 + 8 * j + e]; d1 += kf[e] * qv[(2 * gp + 1) * 64 + 8 * j + e]; } }
;         sc[(2 * gp) * 1040 + n] = d0 * 0.125f; sc[(2 * gp + 1) * 1040 + n] = d1 * 0.125f;
;     }
;     __syncthreads();
	v_mov_b64_e32 v[2:3], v[60:61]
	v_mov_b64_e32 v[4:5], v[62:63]
	v_mov_b64_e32 v[6:7], v[64:65]
	v_mov_b64_e32 v[8:9], v[66:67]
	v_mov_b64_e32 v[10:11], v[68:69]
	v_mov_b64_e32 v[12:13], v[70:71]
	v_mov_b64_e32 v[14:15], v[72:73]
	v_mov_b64_e32 v[16:17], v[74:75]
	ds_read_b128 v[20:23], v136 offset:384
	s_waitcnt vmcnt(0)
	v_lshlrev_b32_e32 v24, 16, v14
	v_and_b32_e32 v25, 0xffff0000, v14
	v_lshlrev_b32_e32 v26, 16, v15
	v_and_b32_e32 v27, 0xffff0000, v15
	v_lshlrev_b32_e32 v28, 16, v16
	v_and_b32_e32 v29, 0xffff0000, v16
	v_lshlrev_b32_e32 v30, 16, v17
	v_and_b32_e32 v31, 0xffff0000, v17
	ds_read_b128 v[14:17], v136 offset:128
	s_waitcnt lgkmcnt(1)
	v_fmac_f32_e32 v19, v20, v24
	v_fmac_f32_e32 v19, v21, v25
	v_fmac_f32_e32 v19, v22, v26
	v_fmac_f32_e32 v19, v23, v27
	s_waitcnt lgkmcnt(0)
	v_fmac_f32_e32 v18, v14, v24
	ds_read_b128 v[20:23], v136 offset:400
	v_fmac_f32_e32 v18, v15, v25
	v_fmac_f32_e32 v18, v16, v26
	v_fmac_f32_e32 v18, v17, v27
	ds_read_b128 v[14:17], v136 offset:144
	s_waitcnt lgkmcnt(1)
	v_fmac_f32_e32 v19, v20, v28
	v_fmac_f32_e32 v19, v21, v29
	v_fmac_f32_e32 v19, v22, v30
	v_fmac_f32_e32 v19, v23, v31
	v_lshlrev_b32_e32 v20, 16, v10
	v_and_b32_e32 v21, 0xffff0000, v10
	v_lshlrev_b32_e32 v22, 16, v11
	v_and_b32_e32 v23, 0xffff0000, v11
	v_lshlrev_b32_e32 v24, 16, v12
	v_and_b32_e32 v25, 0xffff0000, v12
	v_lshlrev_b32_e32 v26, 16, v13
	v_and_b32_e32 v27, 0xffff0000, v13
	ds_read_b128 v[10:13], v136 offset:160
	s_waitcnt lgkmcnt(1)
	v_fmac_f32_e32 v18, v14, v28
	v_fmac_f32_e32 v18, v15, v29
	v_fmac_f32_e32 v18, v16, v30
	v_fmac_f32_e32 v18, v17, v31
	ds_read_b128 v[14:17], v136 offset:416
	s_waitcnt lgkmcnt(1)
	v_fmac_f32_e32 v18, v10, v20
	v_fmac_f32_e32 v18, v11, v21
	v_fmac_f32_e32 v18, v12, v22
	v_fmac_f32_e32 v18, v13, v23
	s_waitcnt lgkmcnt(0)
	v_fmac_f32_e32 v19, v14, v20
	v_fmac_f32_e32 v19, v15, v21
	v_fmac_f32_e32 v19, v16, v22
	v_fmac_f32_e32 v19, v17, v23
	ds_read_b128 v[14:17], v136 offset:432
	ds_read_b128 v[10:13], v136 offset:176
	v_lshlrev_b32_e32 v20, 16, v8
	v_and_b32_e32 v21, 0xffff0000, v8
	v_lshlrev_b32_e32 v22, 16, v9
	s_waitcnt lgkmcnt(1)
	v_fmac_f32_e32 v19, v14, v24
	v_fmac_f32_e32 v19, v15, v25
	v_fmac_f32_e32 v19, v16, v26
	v_fmac_f32_e32 v19, v17, v27
	v_lshlrev_b32_e32 v14, 16, v6
	v_and_b32_e32 v15, 0xffff0000, v6
	v_lshlrev_b32_e32 v16, 16, v7
	v_and_b32_e32 v17, 0xffff0000, v7
	v_and_b32_e32 v23, 0xffff0000, v9
	ds_read_b128 v[6:9], v136 offset:192
	s_waitcnt lgkmcnt(1)
	v_fmac_f32_e32 v18, v10, v24
	v_fmac_f32_e32 v18, v11, v25
	v_fmac_f32_e32 v18, v12, v26
	v_fmac_f32_e32 v18, v13, v27
	ds_read_b128 v[10:13], v136 offset:448
	s_waitcnt lgkmcnt(1)
	v_fmac_f32_e32 v18, v6, v14
	v_fmac_f32_e32 v18, v7, v15
	v_fmac_f32_e32 v18, v8, v16
	v_fmac_f32_e32 v18, v9, v17
	s_waitcnt lgkmcnt(0)
	v_fmac_f32_e32 v19, v10, v14
	v_fmac_f32_e32 v19, v11, v15
	v_fmac_f32_e32 v19, v12, v16
	v_fmac_f32_e32 v19, v13, v17
	ds_read_b128 v[10:13], v136 offset:464
	ds_read_b128 v[6:9], v136 offset:208
	v_lshlrev_b32_e32 v14, 16, v4
	v_and_b32_e32 v15, 0xffff0000, v4
	v_lshlrev_b32_e32 v16, 16, v5
	s_waitcnt lgkmcnt(1)
	v_fmac_f32_e32 v19, v10, v20
	v_fmac_f32_e32 v19, v11, v21
	v_fmac_f32_e32 v19, v12, v22
	v_fmac_f32_e32 v19, v13, v23
	v_lshlrev_b32_e32 v10, 16, v2
	v_and_b32_e32 v11, 0xffff0000, v2
	v_lshlrev_b32_e32 v12, 16, v3
	v_and_b32_e32 v13, 0xffff0000, v3
	v_and_b32_e32 v17, 0xffff0000, v5
	ds_read_b128 v[2:5], v136 offset:224
	s_waitcnt lgkmcnt(1)
	v_fmac_f32_e32 v18, v6, v20
	v_fmac_f32_e32 v18, v7, v21
	v_fmac_f32_e32 v18, v8, v22
	v_fmac_f32_e32 v18, v9, v23
	ds_read_b128 v[6:9], v136 offset:480
	s_waitcnt lgkmcnt(1)
	v_fmac_f32_e32 v18, v2, v10
	v_fmac_f32_e32 v18, v3, v11
	v_fmac_f32_e32 v18, v4, v12
	v_fmac_f32_e32 v18, v5, v13
	ds_read_b128 v[2:5], v136 offset:240
	s_waitcnt lgkmcnt(1)
	v_fmac_f32_e32 v19, v6, v10
	v_fmac_f32_e32 v19, v7, v11
	v_fmac_f32_e32 v19, v8, v12
	v_fmac_f32_e32 v19, v9, v13
	ds_read_b128 v[6:9], v136 offset:496
	s_waitcnt lgkmcnt(1)
	v_fmac_f32_e32 v18, v2, v14
	v_fmac_f32_e32 v18, v3, v15
	v_fmac_f32_e32 v18, v4, v16
	v_fmac_f32_e32 v18, v5, v17
	s_waitcnt lgkmcnt(0)
	v_fmac_f32_e32 v19, v6, v14
	v_fmac_f32_e32 v19, v7, v15
	v_fmac_f32_e32 v19, v8, v16
	v_fmac_f32_e32 v19, v9, v17
	v_mul_f32_e32 v2, 0x3e000000, v18
	ds_write_b32 v137, v2 offset:1024
	v_mul_f32_e32 v2, 0x3e000000, v19
	ds_write_b32 v137, v2 offset:5184
	v_mov_b32_e32 v2, 0xff800000
	v_mov_b32_e32 v3, v148
	v_mov_b32_e32 v4, v147
	s_waitcnt lgkmcnt(0)
	s_barrier

; __device__ __forceinline__ int keypos(int key) { return (key & ~12) | ((key & 4) << 1) | ((key & 8) >> 1); }
; __device__ __forceinline__ void nsa_sample_unit(Frame& F, int l, int unit, int part_id) {
;     ...
;         const int half = tid >> 8, gd = tid & 255, gh = gd >> 6, d = gd & 63;
;         const bf16_t* vt = (const bf16_t*)(F.ws + WS_VCTS) + (size_t)(b * 4 + kvh) * 4 * 4096;
;         float a = 0.f;
;         for (int tl = 2 * half; tl < 2 * half + 2; ++tl) {
;             const bf16_t* vr = vt + (size_t)tl * 4096 + d * 64;
; #pragma unroll
;             for (int j = 0; j < 8; ++j) { const u32x4 x = *(const u32x4*)(vr + 8 * j); float vf[8]; unpack8(x, vf);
; #pragma unroll
;                 for (int e = 0; e < 8; ++e) a += sc[gh * 1040 + tl * 64 + keypos(8 * j + e)] * vf[e]; } }
;         part[half * 256 + gd] = a;
.LBB0_1007:
	s_or_b64 exec, exec, s[22:23]
	v_lshl_add_u64 v[14:15], v[108:109], 0, s[4:5]
	v_lshl_add_u64 v[16:17], v[14:15], 0, v[110:111]
	global_load_dwordx4 v[2:5], v[16:17], off offset:48
	global_load_dwordx4 v[6:9], v[16:17], off offset:32
	global_load_dwordx4 v[10:13], v[16:17], off offset:16
	global_load_dwordx4 v[18:21], v[16:17], off
	v_lshl_add_u64 v[14:15], v[14:15], 0, v[112:113]
	global_load_dwordx4 v[60:63], v[16:17], off offset:112
	global_load_dwordx4 v[64:67], v[16:17], off offset:96
	global_load_dwordx4 v[68:71], v[16:17], off offset:80
	global_load_dwordx4 v[72:75], v[16:17], off offset:64
	global_load_dwordx4 v[76:79], v[14:15], off offset:48
	global_load_dwordx4 v[80:83], v[14:15], off offset:32
	global_load_dwordx4 v[84:87], v[14:15], off offset:16
	global_load_dwordx4 v[88:91], v[14:15], off
	global_load_dwordx4 v[160:163], v[14:15], off offset:112
	global_load_dwordx4 v[164:167], v[14:15], off offset:96
	global_load_dwordx4 v[168:171], v[14:15], off offset:80
	global_load_dwordx4 v[172:175], v[14:15], off offset:64
	s_waitcnt vmcnt(12)
	v_lshlrev_b32_e32 v34, 16, v18
	v_and_b32_e32 v35, 0xffff0000, v18
	v_lshlrev_b32_e32 v36, 16, v19
	v_and_b32_e32 v37, 0xffff0000, v19
	v_lshlrev_b32_e32 v38, 16, v20
	v_and_b32_e32 v39, 0xffff0000, v20
	v_lshlrev_b32_e32 v40, 16, v21
	v_and_b32_e32 v41, 0xffff0000, v21
	ds_read_b128 v[18:21], v138 offset:1024
	ds_read_b128 v[22:25], v138 offset:1040
	ds_read_b128 v[26:29], v138 offset:1056
	ds_read_b128 v[30:33], v138 offset:1072
	s_waitcnt lgkmcnt(3)
	v_fma_f32 v18, v18, v34, 0
	v_fmac_f32_e32 v18, v19, v35
	v_fmac_f32_e32 v18, v20, v36
	v_fmac_f32_e32 v18, v21, v37
	s_waitcnt lgkmcnt(1)
	v_fmac_f32_e32 v18, v26, v38
	v_fmac_f32_e32 v18, v27, v39
	v_fmac_f32_e32 v18, v28, v40
	v_fmac_f32_e32 v18, v29, v41
	v_lshlrev_b32_e32 v19, 16, v10
	v_and_b32_e32 v10, 0xffff0000, v10
	v_fmac_f32_e32 v18, v22, v19
	v_lshlrev_b32_e32 v20, 16, v11
	v_fmac_f32_e32 v18, v23, v10
	v_and_b32_e32 v11, 0xffff0000, v11
	v_fmac_f32_e32 v18, v24, v20
	v_lshlrev_b32_e32 v21, 16, v12
	v_fmac_f32_e32 v18, v25, v11
	v_and_b32_e32 v12, 0xffff0000, v12
	s_waitcnt lgkmcnt(0)
	v_fmac_f32_e32 v18, v30, v21
	v_lshlrev_b32_e32 v26, 16, v13
	v_fmac_f32_e32 v18, v31, v12
	v_and_b32_e32 v13, 0xffff0000, v13
	v_fmac_f32_e32 v18, v32, v26
	v_fmac_f32_e32 v18, v33, v13
	v_lshlrev_b32_e32 v10, 16, v6
	v_and_b32_e32 v11, 0xffff0000, v6
	v_lshlrev_b32_e32 v12, 16, v7
	v_and_b32_e32 v13, 0xffff0000, v7
	v_lshlrev_b32_e32 v19, 16, v8
	v_and_b32_e32 v20, 0xffff0000, v8
	v_lshlrev_b32_e32 v21, 16, v9
	v_and_b32_e32 v22, 0xffff0000, v9
	ds_read_b128 v[6:9], v138 offset:1088
	s_waitcnt lgkmcnt(0)
	v_fmac_f32_e32 v18, v6, v10
	v_fmac_f32_e32 v18, v7, v11
	v_fmac_f32_e32 v18, v8, v12
	v_fmac_f32_e32 v18, v9, v13
	ds_read_b128 v[6:9], v138 offset:1120
	v_lshlrev_b32_e32 v10, 16, v4
	v_and_b32_e32 v11, 0xffff0000, v4
	v_lshlrev_b32_e32 v12, 16, v5
	v_and_b32_e32 v13, 0xffff0000, v5
	s_waitcnt lgkmcnt(0)
	v_fmac_f32_e32 v18, v6, v19
	v_fmac_f32_e32 v18, v7, v20
	v_fmac_f32_e32 v18, v8, v21
	v_fmac_f32_e32 v18, v9, v22
	v_lshlrev_b32_e32 v6, 16, v2
	v_and_b32_e32 v7, 0xffff0000, v2
	v_lshlrev_b32_e32 v8, 16, v3
	v_and_b32_e32 v9, 0xffff0000, v3
	ds_read_b128 v[2:5], v138 offset:1104
	s_waitcnt lgkmcnt(0)
	v_fmac_f32_e32 v18, v2, v6
	v_fmac_f32_e32 v18, v3, v7
	v_fmac_f32_e32 v18, v4, v8
	v_fmac_f32_e32 v18, v5, v9
	ds_read_b128 v[2:5], v138 offset:1136
	s_waitcnt lgkmcnt(0)
	v_fmac_f32_e32 v18, v2, v10
	v_fmac_f32_e32 v18, v3, v11
	v_fmac_f32_e32 v18, v4, v12
	v_fmac_f32_e32 v18, v5, v13
	s_waitcnt vmcnt(8)
	v_mov_b64_e32 v[2:3], v[60:61]
	v_mov_b64_e32 v[4:5], v[62:63]
	v_mov_b64_e32 v[6:7], v[64:65]
	v_mov_b64_e32 v[8:9], v[66:67]
	v_mov_b64_e32 v[10:11], v[68:69]
	v_mov_b64_e32 v[12:13], v[70:71]
	v_mov_b64_e32 v[20:21], v[72:73]
	v_mov_b64_e32 v[22:23], v[74:75]
	v_lshlrev_b32_e32 v16, 16, v20
	v_and_b32_e32 v17, 0xffff0000, v20
	v_lshlrev_b32_e32 v19, 16, v21
	v_and_b32_e32 v24, 0xffff0000, v21
	v_lshlrev_b32_e32 v25, 16, v22
	v_and_b32_e32 v26, 0xffff0000, v22
	v_lshlrev_b32_e32 v27, 16, v23
	v_and_b32_e32 v28, 0xffff0000, v23
	ds_read_b128 v[20:23], v138 offset:1152
	s_waitcnt lgkmcnt(0)
	v_fmac_f32_e32 v18, v20, v16
	v_fmac_f32_e32 v18, v21, v17
	v_fmac_f32_e32 v18, v22, v19
	v_fmac_f32_e32 v18, v23, v24
	ds_read_b128 v[20:23], v138 offset:1184
	v_lshlrev_b32_e32 v16, 16, v10
	v_and_b32_e32 v17, 0xffff0000, v10
	v_lshlrev_b32_e32 v19, 16, v11
	v_and_b32_e32 v24, 0xffff0000, v13
	s_waitcnt lgkmcnt(0)
	v_fmac_f32_e32 v18, v20, v25
	v_fmac_f32_e32 v18, v21, v26
	v_fmac_f32_e32 v18, v22, v27
	v_fmac_f32_e32 v18, v23, v28
	v_and_b32_e32 v20, 0xffff0000, v11
	v_lshlrev_b32_e32 v21, 16, v12
	v_and_b32_e32 v22, 0xffff0000, v12
	v_lshlrev_b32_e32 v23, 16, v13
	ds_read_b128 v[10:13], v138 offset:1168
	s_waitcnt lgkmcnt(0)
	v_fmac_f32_e32 v18, v10, v16
	v_fmac_f32_e32 v18, v11, v17
	v_fmac_f32_e32 v18, v12, v19
	v_fmac_f32_e32 v18, v13, v20
	ds_read_b128 v[10:13], v138 offset:1200
	v_lshlrev_b32_e32 v16, 16, v8
	v_and_b32_e32 v17, 0xffff0000, v8
	v_lshlrev_b32_e32 v19, 16, v9
	v_and_b32_e32 v20, 0xffff0000, v9
	s_waitcnt lgkmcnt(0)
	v_fmac_f32_e32 v18, v10, v21
	v_fmac_f32_e32 v18, v11, v22
	v_fmac_f32_e32 v18, v12, v23
	v_fmac_f32_e32 v18, v13, v24
	v_lshlrev_b32_e32 v10, 16, v6
	v_and_b32_e32 v11, 0xffff0000, v6
	v_lshlrev_b32_e32 v12, 16, v7
	v_and_b32_e32 v13, 0xffff0000, v7
	ds_read_b128 v[6:9], v138 offset:1216
	s_waitcnt lgkmcnt(0)
	v_fmac_f32_e32 v18, v6, v10
	v_fmac_f32_e32 v18, v7, v11
	v_fmac_f32_e32 v18, v8, v12
	v_fmac_f32_e32 v18, v9, v13
	ds_read_b128 v[6:9], v138 offset:1248
	v_lshlrev_b32_e32 v10, 16, v4
	v_and_b32_e32 v11, 0xffff0000, v4
	v_lshlrev_b32_e32 v12, 16, v5
	v_and_b32_e32 v13, 0xffff0000, v5
	s_waitcnt lgkmcnt(0)
; __device__ __forceinline__ int keypos(int key) { return (key & ~12) | ((key & 4) << 1) | ((key & 8) >> 1); }
; __device__ __forceinline__ void nsa_sample_unit(Frame& F, int l, int unit, int part_id) {
;     ...
;         for (int tl = 2 * half; tl < 2 * half + 2; ++tl) {
;             const bf16_t* vr = vt + (size_t)tl * 4096 + d * 64;
; #pragma unroll
;             for (int j = 0; j < 8; ++j) { const u32x4 x = *(const u32x4*)(vr + 8 * j); float vf[8]; unpack8(x, vf);
; #pragma unroll
;                 for (int e = 0; e < 8; ++e) a += sc[gh * 1040 + tl * 64 + keypos(8 * j + e)] * vf[e]; } }
;         part[half * 256 + gd] = a;
;     }
;     __syncthreads();
;     if (tid < 256) oacc[tid] = part[tid] + part[256 + tid];
	v_fmac_f32_e32 v18, v6, v16
	v_fmac_f32_e32 v18, v7, v17
	v_fmac_f32_e32 v18, v8, v19
	v_fmac_f32_e32 v18, v9, v20
	v_lshlrev_b32_e32 v6, 16, v2
	v_and_b32_e32 v7, 0xffff0000, v2
	v_lshlrev_b32_e32 v8, 16, v3
	v_and_b32_e32 v9, 0xffff0000, v3
	ds_read_b128 v[2:5], v138 offset:1232
	s_waitcnt lgkmcnt(0)
	v_fmac_f32_e32 v18, v2, v6
	v_fmac_f32_e32 v18, v3, v7
	v_fmac_f32_e32 v18, v4, v8
	v_fmac_f32_e32 v18, v5, v9
	ds_read_b128 v[2:5], v138 offset:1264
	s_waitcnt lgkmcnt(0)
	v_fmac_f32_e32 v18, v2, v10
	v_fmac_f32_e32 v18, v3, v11
	v_fmac_f32_e32 v18, v4, v12
	v_fmac_f32_e32 v18, v5, v13
	s_waitcnt vmcnt(4)
	v_mov_b64_e32 v[2:3], v[76:77]
	v_mov_b64_e32 v[4:5], v[78:79]
	v_mov_b64_e32 v[6:7], v[80:81]
	v_mov_b64_e32 v[8:9], v[82:83]
	v_mov_b64_e32 v[10:11], v[84:85]
	v_mov_b64_e32 v[12:13], v[86:87]
	v_mov_b64_e32 v[20:21], v[88:89]
	v_mov_b64_e32 v[22:23], v[90:91]
	v_lshlrev_b32_e32 v16, 16, v20
	v_and_b32_e32 v17, 0xffff0000, v20
	v_lshlrev_b32_e32 v19, 16, v21
	v_and_b32_e32 v36, 0xffff0000, v21
	v_lshlrev_b32_e32 v37, 16, v22
	v_and_b32_e32 v38, 0xffff0000, v22
	v_lshlrev_b32_e32 v39, 16, v23
	v_and_b32_e32 v40, 0xffff0000, v23
	ds_read_b128 v[20:23], v139 offset:1024
	ds_read_b128 v[24:27], v139 offset:1040
	ds_read_b128 v[28:31], v139 offset:1056
	ds_read_b128 v[32:35], v139 offset:1072
	s_waitcnt lgkmcnt(3)
	v_fmac_f32_e32 v18, v20, v16
	v_fmac_f32_e32 v18, v21, v17
	v_fmac_f32_e32 v18, v22, v19
	v_fmac_f32_e32 v18, v23, v36
	s_waitcnt lgkmcnt(1)
	v_fmac_f32_e32 v18, v28, v37
	v_fmac_f32_e32 v18, v29, v38
	v_fmac_f32_e32 v18, v30, v39
	v_fmac_f32_e32 v18, v31, v40
	v_lshlrev_b32_e32 v16, 16, v10
	v_and_b32_e32 v10, 0xffff0000, v10
	v_fmac_f32_e32 v18, v24, v16
	v_lshlrev_b32_e32 v17, 16, v11
	v_fmac_f32_e32 v18, v25, v10
	v_and_b32_e32 v11, 0xffff0000, v11
	v_fmac_f32_e32 v18, v26, v17
	v_lshlrev_b32_e32 v19, 16, v12
	v_fmac_f32_e32 v18, v27, v11
	v_and_b32_e32 v12, 0xffff0000, v12
	s_waitcnt lgkmcnt(0)
	v_fmac_f32_e32 v18, v32, v19
	v_lshlrev_b32_e32 v20, 16, v13
	v_fmac_f32_e32 v18, v33, v12
	v_and_b32_e32 v13, 0xffff0000, v13
	v_fmac_f32_e32 v18, v34, v20
	v_fmac_f32_e32 v18, v35, v13
	v_lshlrev_b32_e32 v10, 16, v6
	v_and_b32_e32 v11, 0xffff0000, v6
	v_lshlrev_b32_e32 v12, 16, v7
	v_and_b32_e32 v13, 0xffff0000, v7
	v_lshlrev_b32_e32 v16, 16, v8
	v_and_b32_e32 v17, 0xffff0000, v8
	v_lshlrev_b32_e32 v19, 16, v9
	v_and_b32_e32 v20, 0xffff0000, v9
	ds_read_b128 v[6:9], v139 offset:1088
	s_waitcnt lgkmcnt(0)
	v_fmac_f32_e32 v18, v6, v10
	v_fmac_f32_e32 v18, v7, v11
	v_fmac_f32_e32 v18, v8, v12
	v_fmac_f32_e32 v18, v9, v13
	ds_read_b128 v[6:9], v139 offset:1120
	v_lshlrev_b32_e32 v10, 16, v4
	v_and_b32_e32 v11, 0xffff0000, v4
	v_lshlrev_b32_e32 v12, 16, v5
	v_and_b32_e32 v13, 0xffff0000, v5
	s_waitcnt lgkmcnt(0)
	v_fmac_f32_e32 v18, v6, v16
	v_fmac_f32_e32 v18, v7, v17
	v_fmac_f32_e32 v18, v8, v19
	v_fmac_f32_e32 v18, v9, v20
	v_lshlrev_b32_e32 v6, 16, v2
	v_and_b32_e32 v7, 0xffff0000, v2
	v_lshlrev_b32_e32 v8, 16, v3
	v_and_b32_e32 v9, 0xffff0000, v3
	ds_read_b128 v[2:5], v139 offset:1104
	s_waitcnt lgkmcnt(0)
	v_fmac_f32_e32 v18, v2, v6
	v_fmac_f32_e32 v18, v3, v7
	v_fmac_f32_e32 v18, v4, v8
	v_fmac_f32_e32 v18, v5, v9
	ds_read_b128 v[2:5], v139 offset:1136
	s_waitcnt lgkmcnt(0)
	v_fmac_f32_e32 v18, v2, v10
	v_fmac_f32_e32 v18, v3, v11
	v_fmac_f32_e32 v18, v4, v12
	v_fmac_f32_e32 v18, v5, v13
	s_waitcnt vmcnt(0)
	v_mov_b64_e32 v[2:3], v[160:161]
	v_mov_b64_e32 v[4:5], v[162:163]
	v_mov_b64_e32 v[6:7], v[164:165]
	v_mov_b64_e32 v[8:9], v[166:167]
	v_mov_b64_e32 v[10:11], v[168:169]
	v_mov_b64_e32 v[12:13], v[170:171]
	v_mov_b64_e32 v[14:15], v[172:173]
	v_mov_b64_e32 v[16:17], v[174:175]
	s_waitcnt vmcnt(0)
	v_lshlrev_b32_e32 v19, 16, v14
	v_and_b32_e32 v20, 0xffff0000, v14
	v_lshlrev_b32_e32 v21, 16, v15
	v_and_b32_e32 v22, 0xffff0000, v15
	v_lshlrev_b32_e32 v23, 16, v16
	v_and_b32_e32 v24, 0xffff0000, v16
	v_lshlrev_b32_e32 v25, 16, v17
	v_and_b32_e32 v26, 0xffff0000, v17
	ds_read_b128 v[14:17], v139 offset:1152
	s_waitcnt lgkmcnt(0)
	v_fmac_f32_e32 v18, v14, v19
	v_fmac_f32_e32 v18, v15, v20
	v_fmac_f32_e32 v18, v16, v21
	v_fmac_f32_e32 v18, v17, v22
	ds_read_b128 v[14:17], v139 offset:1184
	v_lshlrev_b32_e32 v19, 16, v12
	v_and_b32_e32 v20, 0xffff0000, v12
	v_lshlrev_b32_e32 v21, 16, v13
	v_and_b32_e32 v22, 0xffff0000, v13
	s_waitcnt lgkmcnt(0)
	v_fmac_f32_e32 v18, v14, v23
	v_fmac_f32_e32 v18, v15, v24
	v_fmac_f32_e32 v18, v16, v25
	v_fmac_f32_e32 v18, v17, v26
	v_lshlrev_b32_e32 v14, 16, v10
	v_and_b32_e32 v15, 0xffff0000, v10
	v_lshlrev_b32_e32 v16, 16, v11
	v_and_b32_e32 v17, 0xffff0000, v11
	ds_read_b128 v[10:13], v139 offset:1168
	s_waitcnt lgkmcnt(0)
	v_fmac_f32_e32 v18, v10, v14
	v_fmac_f32_e32 v18, v11, v15
	v_fmac_f32_e32 v18, v12, v16
	v_fmac_f32_e32 v18, v13, v17
	ds_read_b128 v[10:13], v139 offset:1200
	v_lshlrev_b32_e32 v14, 16, v6
	v_and_b32_e32 v6, 0xffff0000, v6
	v_lshlrev_b32_e32 v15, 16, v7
	v_and_b32_e32 v7, 0xffff0000, v7
	s_waitcnt lgkmcnt(0)
	v_fmac_f32_e32 v18, v10, v19
	v_fmac_f32_e32 v18, v11, v20
	v_fmac_f32_e32 v18, v12, v21
	v_fmac_f32_e32 v18, v13, v22
	ds_read_b128 v[10:13], v139 offset:1216
	s_waitcnt lgkmcnt(0)
	v_fmac_f32_e32 v18, v10, v14
	v_fmac_f32_e32 v18, v11, v6
	v_fmac_f32_e32 v18, v12, v15
	v_fmac_f32_e32 v18, v13, v7
	ds_read_b128 v[10:13], v139 offset:1248
	v_and_b32_e32 v7, 0xffff0000, v8
	v_lshlrev_b32_e32 v6, 16, v8
	s_waitcnt lgkmcnt(0)
	v_pk_mul_f32 v[6:7], v[10:11], v[6:7]
	s_nop 0
	v_add_f32_e32 v6, v6, v18
	v_add_f32_e32 v8, v7, v6
	v_and_b32_e32 v7, 0xffff0000, v9
	v_lshlrev_b32_e32 v6, 16, v9
	v_pk_mul_f32 v[6:7], v[12:13], v[6:7]
	v_and_b32_e32 v11, 0xffff0000, v2
	v_add_f32_e32 v6, v6, v8
	v_add_f32_e32 v12, v7, v6
	ds_read_b128 v[6:9], v139 offset:1232
	v_lshlrev_b32_e32 v10, 16, v2
	s_waitcnt lgkmcnt(0)
	v_pk_mul_f32 v[6:7], v[6:7], v[10:11]
	s_nop 0
	v_add_f32_e32 v2, v12, v6
	v_add_f32_e32 v10, v7, v2
	v_and_b32_e32 v7, 0xffff0000, v3
	v_lshlrev_b32_e32 v6, 16, v3
	v_pk_mul_f32 v[2:3], v[8:9], v[6:7]
	ds_read_b128 v[6:9], v139 offset:1264
	v_add_f32_e32 v2, v2, v10
	v_add_f32_e32 v10, v3, v2
	v_and_b32_e32 v3, 0xffff0000, v4
	v_lshlrev_b32_e32 v2, 16, v4
	s_waitcnt lgkmcnt(0)
	v_pk_mul_f32 v[2:3], v[6:7], v[2:3]
	s_nop 0
	v_add_f32_e32 v2, v2, v10
	v_add_f32_e32 v4, v3, v2
	v_and_b32_e32 v3, 0xffff0000, v5
	v_lshlrev_b32_e32 v2, 16, v5
	v_pk_mul_f32 v[2:3], v[8:9], v[2:3]
	s_nop 0
	v_add_f32_e32 v2, v2, v4
	v_add_f32_e32 v2, v3, v2
	ds_write_b32 v115, v2 offset:23072
	s_waitcnt lgkmcnt(0)
	s_barrier
	s_and_saveexec_b64 s[22:23], s[44:45]
	s_cbranch_execz .LBB0_1009
	v_add_u32_e32 v2, 32, v115
	ds_read2st64_b32 v[2:3], v2 offset0:90 offset1:94
	s_waitcnt lgkmcnt(0)
	v_add_f32_e32 v2, v2, v3
	ds_write_b32 v115, v2 offset:55840
